# windowed attention: ALiBi -slope*|d| via v_fma_f32 with |.| source modifier instead of v_and + v_pk_fma (same per-element f32 fma)
# speedup vs baseline: 1.0091x; 1.0091x over previous
; #define MFMA32(a, b, c) __builtin_amdgcn_mfma_f32_32x32x16_bf16((a), (b), (c), 0, 0, 0)
; template <int MODE>
; DI void attn_item(const Params& p, int layer, int b, int hq, int qb, u16* lds, const int WAVE_S) {
;     ...
;     bool live = true;
;     if (MODE == 1) {
;       const int kb = kbase0 + t * 64;
;       const int gap = (kb > q0 + 31) ? kb - (q0 + 31) : ((kb + 63 < q0) ? q0 - (kb + 63) : 0);
;       live = gap <= 128;
;     }
;     if (live) {
;     f32x16 sc[2];
; #pragma unroll
;     for (int k2 = 0; k2 < 2; ++k2) {
; #pragma unroll
;       for (int ks = 0; ks < 4; ++ks) {
;         const bf16x8 kf = *(const bf16x8*)(Ks + (k2 * 32 + r) * LSTR + ks * 16 + h * 8);
;         sc[k2] = (ks == 0) ? MFMA32(kf, qf[0], negm) : MFMA32(kf, qf[ks], sc[k2]);
;       }
;     }
;     if (MODE == 1) {
;       const float tposf = (float)(q0 + r - (kbase0 + t * 64) - 4 * h);
; #pragma unroll
;       for (int k2 = 0; k2 < 2; ++k2)
; #pragma unroll
;         for (int i = 0; i < 16; ++i) {
;           const float dist = fabsf(tposf - (float)(k2 * 32 + (i & 3) + 8 * (i >> 2)));
;           sc[k2][i] = (dist <= 128.f) ? (sc[k2][i] - slope2 * dist) : -1e30f;
;         }
;     }
;     float mx0 = fmaxf(fmaxf(sc[0][0], sc[0][1]), sc[0][2]), mx1 = fmaxf(fmaxf(sc[1][0], sc[1][1]), sc[1][2]);
; #pragma unroll
;     for (int i = 3; i < 15; i += 2) { mx0 = fmaxf(fmaxf(mx0, sc[0][i]), sc[0][i + 1]); mx1 = fmaxf(fmaxf(mx1, sc[1][i]), sc[1][i + 1]); }
;     float mx = fmaxf(fmaxf(mx0, mx1), fmaxf(sc[0][15], sc[1][15]));
.LBB0_184:
	v_max_i32_e32 v50, s85, v116
	v_add_u32_e32 v50, s96, v50
	v_cmp_gt_i32_e32 vcc, s34, v130
	s_and_saveexec_b64 s[18:19], vcc
	s_lshl_b32 s44, s28, 6
	s_add_i32 s44, s44, s84
	v_sub_u32_e32 v50, s44, v130
	s_or_b64 exec, exec, s[18:19]
	s_movk_i32 s18, 0x81
	v_cmp_gt_i32_e32 vcc, s18, v50
	s_and_saveexec_b64 s[44:45], vcc
	s_cbranch_execz .LBB0_180
	s_and_b32 s18, s97, 0x80
	s_mulk_i32 s18, 0x90
	v_add_u32_e32 v133, s18, v131
	ds_read_b128 v[50:53], v133
	ds_read_b128 v[54:57], v133 offset:32
	ds_read_b128 v[134:137], v133 offset:4608
	v_cvt_f32_i32_e32 v128, v132
	s_waitcnt lgkmcnt(2)
	v_mfma_f32_32x32x16_bf16 v[66:81], v[50:53], v[82:85], v[2:17]
	ds_read_b128 v[50:53], v133 offset:64
	s_waitcnt lgkmcnt(2)
	v_mfma_f32_32x32x16_bf16 v[66:81], v[54:57], v[86:89], v[66:81]
	s_waitcnt lgkmcnt(0)
	v_mfma_f32_32x32x16_bf16 v[66:81], v[50:53], v[90:93], v[66:81]
	ds_read_b128 v[50:53], v133 offset:96
	s_waitcnt lgkmcnt(0)
	v_mfma_f32_32x32x16_bf16 v[66:81], v[50:53], v[94:97], v[66:81]
	v_mov_b64_e32 v[64:65], v[16:17]
	v_mov_b64_e32 v[62:63], v[14:15]
	v_mov_b64_e32 v[60:61], v[12:13]
	v_mov_b64_e32 v[58:59], v[10:11]
	v_mov_b64_e32 v[56:57], v[8:9]
	v_mov_b64_e32 v[54:55], v[6:7]
	v_mov_b64_e32 v[52:53], v[4:5]
	v_mov_b64_e32 v[50:51], v[2:3]
	s_nop 1
	v_mfma_f32_32x32x16_bf16 v[50:65], v[134:137], v[82:85], v[50:65]
	ds_read_b128 v[134:137], v133 offset:4640
	s_waitcnt lgkmcnt(0)
	v_mfma_f32_32x32x16_bf16 v[50:65], v[134:137], v[86:89], v[50:65]
	ds_read_b128 v[134:137], v133 offset:4672
	s_waitcnt lgkmcnt(0)
	v_mfma_f32_32x32x16_bf16 v[50:65], v[134:137], v[90:93], v[50:65]
	ds_read_b128 v[134:137], v133 offset:4704
	s_waitcnt lgkmcnt(0)
	v_mfma_f32_32x32x16_bf16 v[50:65], v[134:137], v[94:97], v[50:65]
	v_add_f32_e32 v136, -1.0, v128
	s_nop 0
	s_nop 0
	v_fma_f32 v134, -v120, |v128|, v66
	v_fma_f32 v135, -v121, |v136|, v67
	v_cmp_le_f32_e64 vcc, |v136|, s89
	s_nop 1
	v_cndmask_b32_e32 v66, v146, v135, vcc
	v_cmp_le_f32_e64 vcc, |v128|, s89
	s_nop 1
	v_cndmask_b32_e32 v67, v146, v134, vcc
	v_pk_add_f32 v[134:135], v[128:129], s[2:3] op_sel_hi:[0,1]
	s_nop 0
	s_nop 0
	v_fma_f32 v136, -v120, |v134|, v68
	v_fma_f32 v137, -v121, |v135|, v69
	v_cmp_le_f32_e64 vcc, |v135|, s89
	s_nop 1
	v_cndmask_b32_e32 v68, v146, v137, vcc
	v_cmp_le_f32_e64 vcc, |v134|, s89
	v_pk_add_f32 v[134:135], v[128:129], s[38:39] op_sel_hi:[0,1]
	s_nop 0
	v_cndmask_b32_e32 v69, v146, v136, vcc
	s_nop 0
	v_fma_f32 v136, -v120, |v134|, v70
	v_fma_f32 v137, -v121, |v135|, v71
	v_cmp_le_f32_e64 vcc, |v135|, s89
	s_nop 1
	v_cndmask_b32_e32 v70, v146, v137, vcc
	v_cmp_le_f32_e64 vcc, |v134|, s89
	v_pk_add_f32 v[134:135], v[128:129], s[4:5] op_sel_hi:[0,1]
	s_nop 0
	v_cndmask_b32_e32 v71, v146, v136, vcc
	s_nop 0
	v_fma_f32 v136, -v120, |v134|, v72
	v_fma_f32 v137, -v121, |v135|, v73
	v_cmp_le_f32_e64 vcc, |v135|, s89
	s_nop 1
	v_cndmask_b32_e32 v72, v146, v137, vcc
	v_cmp_le_f32_e64 vcc, |v134|, s89
	v_pk_add_f32 v[134:135], v[128:129], s[52:53] op_sel_hi:[0,1]
	s_nop 0
	v_cndmask_b32_e32 v73, v146, v136, vcc
	s_nop 0
	v_fma_f32 v136, -v120, |v134|, v74
	v_fma_f32 v137, -v121, |v135|, v75
	v_cmp_le_f32_e64 vcc, |v135|, s89
	s_nop 1
	v_cndmask_b32_e32 v74, v146, v137, vcc
	v_cmp_le_f32_e64 vcc, |v134|, s89
	v_pk_add_f32 v[134:135], v[128:129], s[26:27] op_sel_hi:[0,1]
	s_nop 0
	v_cndmask_b32_e32 v75, v146, v136, vcc
	s_nop 0
	v_fma_f32 v136, -v120, |v134|, v76
	v_fma_f32 v137, -v121, |v135|, v77
	v_cmp_le_f32_e64 vcc, |v135|, s89
	s_nop 1
	v_cndmask_b32_e32 v76, v146, v137, vcc
	v_cmp_le_f32_e64 vcc, |v134|, s89
	v_pk_add_f32 v[134:135], v[128:129], s[76:77] op_sel_hi:[0,1]
	s_nop 0
	v_cndmask_b32_e32 v77, v146, v136, vcc
	s_nop 0
	v_fma_f32 v136, -v120, |v134|, v78
	v_fma_f32 v137, -v121, |v135|, v79
	v_cmp_le_f32_e64 vcc, |v135|, s89
	s_nop 1
	v_cndmask_b32_e32 v78, v146, v137, vcc
	v_cmp_le_f32_e64 vcc, |v134|, s89
	v_pk_add_f32 v[134:135], v[128:129], s[22:23] op_sel_hi:[0,1]
	s_nop 0
	v_cndmask_b32_e32 v79, v146, v136, vcc
	s_nop 0
	v_fma_f32 v136, -v120, |v134|, v80
	v_fma_f32 v137, -v121, |v135|, v81
	v_cmp_le_f32_e64 vcc, |v135|, s89
	s_nop 1
	v_cndmask_b32_e32 v80, v146, v137, vcc
	v_cmp_le_f32_e64 vcc, |v134|, s89
	v_pk_add_f32 v[134:135], v[128:129], s[10:11] op_sel_hi:[0,1]
	s_nop 0
	v_cndmask_b32_e32 v81, v146, v136, vcc
	s_nop 0
	v_fma_f32 v136, -v120, |v134|, v50
	v_fma_f32 v137, -v121, |v135|, v51
	v_cmp_le_f32_e64 vcc, |v135|, s89
	s_nop 1
	v_cndmask_b32_e32 v50, v146, v137, vcc
	v_cmp_le_f32_e64 vcc, |v134|, s89
	v_pk_add_f32 v[134:135], v[128:129], s[30:31] op_sel_hi:[0,1]
	s_nop 0
	v_cndmask_b32_e32 v51, v146, v136, vcc
	s_nop 0
	v_fma_f32 v136, -v120, |v134|, v52
	v_fma_f32 v137, -v121, |v135|, v53
	v_cmp_le_f32_e64 vcc, |v135|, s89
	s_nop 1
	v_cndmask_b32_e32 v52, v146, v137, vcc
	v_cmp_le_f32_e64 vcc, |v134|, s89
	v_pk_add_f32 v[134:135], v[128:129], s[20:21] op_sel_hi:[0,1]
	s_nop 0
	v_cndmask_b32_e32 v53, v146, v136, vcc
; template <int MODE>
; DI void attn_item(const Params& p, int layer, int b, int hq, int qb, u16* lds, const int WAVE_S) {
;     ...
;     if (MODE == 1) {
;       const float tposf = (float)(q0 + r - (kbase0 + t * 64) - 4 * h);
; #pragma unroll
;       for (int k2 = 0; k2 < 2; ++k2)
; #pragma unroll
;         for (int i = 0; i < 16; ++i) {
;           const float dist = fabsf(tposf - (float)(k2 * 32 + (i & 3) + 8 * (i >> 2)));
;           sc[k2][i] = (dist <= 128.f) ? (sc[k2][i] - slope2 * dist) : -1e30f;
;         }
;     }
;     float mx0 = fmaxf(fmaxf(sc[0][0], sc[0][1]), sc[0][2]), mx1 = fmaxf(fmaxf(sc[1][0], sc[1][1]), sc[1][2]);
; #pragma unroll
;     for (int i = 3; i < 15; i += 2) { mx0 = fmaxf(fmaxf(mx0, sc[0][i]), sc[0][i + 1]); mx1 = fmaxf(fmaxf(mx1, sc[1][i]), sc[1][i + 1]); }
;     float mx = fmaxf(fmaxf(mx0, mx1), fmaxf(sc[0][15], sc[1][15]));
;     {
;       auto rr = __builtin_amdgcn_permlane32_swap(__float_as_uint(mx), __float_as_uint(mx), false, false);
;       mx = fmaxf(__uint_as_float(rr[0]), __uint_as_float(rr[1]));
;     }
;     if (__any(mx > 8.0f)) {
;       const float delta = fmaxf(mx, 0.f);
;       const float al = __builtin_amdgcn_exp2f(-delta);
; #pragma unroll
;       for (int k2 = 0; k2 < 2; ++k2)
; #pragma unroll
;         for (int i = 0; i < 16; ++i) sc[k2][i] -= delta;
; #pragma unroll
;       for (int dt = 0; dt < 2; ++dt)
; #pragma unroll
;         for (int i = 0; i < 16; ++i) o[dt][i] *= al;
;       l_run *= al;
;       m_run += delta;
; #pragma unroll
;       for (int i = 0; i < 16; ++i) negm[i] = -m_run;
;     }
	s_nop 0
	v_fma_f32 v136, -v120, |v134|, v54
	v_fma_f32 v137, -v121, |v135|, v55
	v_cmp_le_f32_e64 vcc, |v135|, s89
	s_nop 1
	v_cndmask_b32_e32 v54, v146, v137, vcc
	v_cmp_le_f32_e64 vcc, |v134|, s89
	v_pk_add_f32 v[134:135], v[128:129], s[6:7] op_sel_hi:[0,1]
	s_nop 0
	v_cndmask_b32_e32 v55, v146, v136, vcc
	s_nop 0
	v_fma_f32 v136, -v120, |v134|, v56
	v_fma_f32 v137, -v121, |v135|, v57
	v_cmp_le_f32_e64 vcc, |v135|, s89
	s_nop 1
	v_cndmask_b32_e32 v56, v146, v137, vcc
	v_cmp_le_f32_e64 vcc, |v134|, s89
	v_pk_add_f32 v[134:135], v[128:129], s[42:43] op_sel_hi:[0,1]
	s_nop 0
	v_cndmask_b32_e32 v57, v146, v136, vcc
	s_nop 0
	v_fma_f32 v136, -v120, |v134|, v58
	v_fma_f32 v137, -v121, |v135|, v59
	v_cmp_le_f32_e64 vcc, |v135|, s89
	s_nop 1
	v_cndmask_b32_e32 v58, v146, v137, vcc
	v_cmp_le_f32_e64 vcc, |v134|, s89
	v_pk_add_f32 v[134:135], v[128:129], s[14:15] op_sel_hi:[0,1]
	s_nop 0
	v_cndmask_b32_e32 v59, v146, v136, vcc
	s_nop 0
	v_fma_f32 v136, -v120, |v134|, v60
	v_fma_f32 v137, -v121, |v135|, v61
	v_cmp_le_f32_e64 vcc, |v135|, s89
	s_nop 1
	v_cndmask_b32_e32 v60, v146, v137, vcc
	v_cmp_le_f32_e64 vcc, |v134|, s89
	v_pk_add_f32 v[134:135], v[128:129], s[82:83] op_sel_hi:[0,1]
	s_nop 0
	v_cndmask_b32_e32 v61, v146, v136, vcc
	s_nop 0
	v_fma_f32 v136, -v120, |v134|, v62
	v_fma_f32 v137, -v121, |v135|, v63
	v_cmp_le_f32_e64 vcc, |v135|, s89
	s_nop 1
	v_cndmask_b32_e32 v62, v146, v137, vcc
	v_cmp_le_f32_e64 vcc, |v134|, s89
	v_pk_add_f32 v[134:135], v[128:129], s[8:9] op_sel_hi:[0,1]
	s_nop 0
	v_cndmask_b32_e32 v63, v146, v136, vcc
	s_nop 0
	v_fma_f32 v136, -v120, |v134|, v64
	v_fma_f32 v137, -v121, |v135|, v65
	v_cmp_le_f32_e64 vcc, |v135|, s89
	v_max3_f32 v128, v67, v66, v69
	v_max3_f32 v128, v128, v68, v71
	v_cndmask_b32_e32 v64, v146, v137, vcc
	v_cmp_le_f32_e64 vcc, |v134|, s89
	v_max3_f32 v134, v51, v50, v53
	v_max3_f32 v134, v134, v52, v55
	v_max3_f32 v128, v128, v70, v73
	v_max3_f32 v134, v134, v54, v57
	v_max3_f32 v128, v128, v72, v75
	v_max3_f32 v134, v134, v56, v59
	v_max3_f32 v128, v128, v74, v77
	v_max3_f32 v134, v134, v58, v61
	v_cndmask_b32_e32 v65, v146, v136, vcc
	v_max3_f32 v128, v128, v76, v79
	v_max3_f32 v134, v134, v60, v63
	v_max3_f32 v128, v128, v78, v81
	v_max3_f32 v134, v134, v62, v65
	v_max_f32_e32 v135, v80, v64
	v_max3_f32 v128, v128, v134, v135
	v_mov_b32_e32 v134, v128
	s_nop 1
	v_permlane32_swap_b32_e32 v128, v134
	v_max_f32_e32 v134, v134, v134
	v_max_f32_e32 v128, v128, v128
	v_max_f32_e32 v128, v128, v134
	v_cmp_lt_f32_e32 vcc, s90, v128
	s_cbranch_vccz .LBB0_179
	v_max_f32_e32 v2, v128, v128
	v_max_f32_e32 v2, 0, v2
	v_exp_f32_e64 v4, -v2
	v_add_f32_e32 v115, v115, v2
	v_sub_f32_e32 v67, v67, v2
	v_sub_f32_e32 v66, v66, v2
	v_sub_f32_e32 v69, v69, v2
	v_sub_f32_e32 v68, v68, v2
	v_sub_f32_e32 v71, v71, v2
	v_sub_f32_e32 v70, v70, v2
	v_sub_f32_e32 v73, v73, v2
	v_sub_f32_e32 v72, v72, v2
	v_sub_f32_e32 v75, v75, v2
	v_sub_f32_e32 v74, v74, v2
	v_sub_f32_e32 v77, v77, v2
	v_sub_f32_e32 v76, v76, v2
	v_sub_f32_e32 v79, v79, v2
	v_sub_f32_e32 v78, v78, v2
	v_sub_f32_e32 v81, v81, v2
	v_sub_f32_e32 v80, v80, v2
	v_sub_f32_e32 v51, v51, v2
	v_sub_f32_e32 v50, v50, v2
	v_sub_f32_e32 v53, v53, v2
	v_sub_f32_e32 v52, v52, v2
	v_sub_f32_e32 v55, v55, v2
	v_sub_f32_e32 v54, v54, v2
	v_sub_f32_e32 v57, v57, v2
	v_sub_f32_e32 v56, v56, v2
	v_sub_f32_e32 v59, v59, v2
	v_sub_f32_e32 v58, v58, v2
	v_sub_f32_e32 v61, v61, v2
	v_sub_f32_e32 v60, v60, v2
	v_sub_f32_e32 v63, v63, v2
	v_sub_f32_e32 v62, v62, v2
	v_sub_f32_e32 v65, v65, v2
	v_sub_f32_e32 v64, v64, v2
	v_xor_b32_e32 v2, 0x80000000, v115
	v_pk_mul_f32 v[32:33], v[32:33], v[4:5] op_sel_hi:[1,0]
	v_pk_mul_f32 v[30:31], v[30:31], v[4:5] op_sel_hi:[1,0]
	v_pk_mul_f32 v[28:29], v[28:29], v[4:5] op_sel_hi:[1,0]
	v_pk_mul_f32 v[26:27], v[26:27], v[4:5] op_sel_hi:[1,0]
	v_pk_mul_f32 v[24:25], v[24:25], v[4:5] op_sel_hi:[1,0]
	v_pk_mul_f32 v[22:23], v[22:23], v[4:5] op_sel_hi:[1,0]
	v_pk_mul_f32 v[20:21], v[20:21], v[4:5] op_sel_hi:[1,0]
	v_pk_mul_f32 v[18:19], v[18:19], v[4:5] op_sel_hi:[1,0]
	v_pk_mul_f32 v[48:49], v[48:49], v[4:5] op_sel_hi:[1,0]
	v_pk_mul_f32 v[46:47], v[46:47], v[4:5] op_sel_hi:[1,0]
	v_pk_mul_f32 v[44:45], v[44:45], v[4:5] op_sel_hi:[1,0]
	v_pk_mul_f32 v[42:43], v[42:43], v[4:5] op_sel_hi:[1,0]
	v_pk_mul_f32 v[40:41], v[40:41], v[4:5] op_sel_hi:[1,0]
	v_pk_mul_f32 v[38:39], v[38:39], v[4:5] op_sel_hi:[1,0]
	v_pk_mul_f32 v[36:37], v[36:37], v[4:5] op_sel_hi:[1,0]
	v_pk_mul_f32 v[34:35], v[34:35], v[4:5] op_sel_hi:[1,0]
	v_mul_f32_e32 v129, v129, v4
	v_mov_b32_e32 v3, v2
	v_mov_b32_e32 v4, v2
	v_mov_b32_e32 v5, v2
	v_mov_b32_e32 v6, v2
	v_mov_b32_e32 v7, v2
	v_mov_b32_e32 v8, v2
	v_mov_b32_e32 v9, v2
	v_mov_b32_e32 v10, v2
	v_mov_b32_e32 v11, v2
	v_mov_b32_e32 v12, v2
	v_mov_b32_e32 v13, v2
	v_mov_b32_e32 v14, v2
	v_mov_b32_e32 v15, v2
	v_mov_b32_e32 v16, v2
	v_mov_b32_e32 v17, v2
	s_branch .LBB0_179
